# mix1 knorm relayout: one dword (2 bf16) per lane, both heads per instruction, per-element butterfly chains kept (in-lane + DPP quad_perm/row_ror + 2 bpermute steps), packed dword stores: half the knor
# speedup vs baseline: 1.0055x; 1.0055x over previous
; __device__ __forceinline__ float bf2f(unsigned short u) { return __uint_as_float((unsigned)u << 16); }
; __device__ __forceinline__ void knorm_item(const KArgs& a, int l, int item, int wave, int lane) {
;     const bf16_t* Z = (const bf16_t*)(a.ws + WS_Z);
;     const float kg = a.in[I_KN][l * 64 + lane];
;     for (int r0 = 0; r0 < 128; r0 += 16) {
;         float v[16];
; #pragma unroll
;         for (int i = 0; i < 16; ++i) { const int task = item * 1024 + wave * 128 + r0 + i, row = task >> 2, which = (task >> 1) & 1, g = task & 1;
;             v[i] = bf2f(Z[(size_t)row * ZW + (which ? ZC_KW : ZC_KS) + g * 64 + lane]); }
; #pragma unroll
;         for (int i = 0; i < 16; ++i) { const int task = item * 1024 + wave * 128 + r0 + i, row = task >> 2, which = (task >> 1) & 1, g = task & 1;
;             const float rstd = rsqrtf(wave_sum(v[i] * v[i]) * (1.f / 64.f) + EPS);
; __device__ __forceinline__ void phase_mix1(const KArgs& a, int l, LAS unsigned char* lds, int wave, int lane, int ci) {
;     ...
;     for (;;) {
;         __syncthreads();
;         if (threadIdx.x == 0) *slot = (int)atomicAdd(ctr, 1u);
;         __syncthreads();
;         int r = *slot;
;         if (r >= N_R0 + N_CMP + N_CONV + N_KN) break;
;         if (r < N_R0) { ret0_item(a, l, r, lds, wave, lane); continue; } r -= N_R0;
;         if (r < N_CMP) { cmp_mfma_item(a, l, r, lds, wave, lane); continue; } r -= N_CMP;
;         if (r < N_CONV) { conv_item(a, l, r); continue; } r -= N_CONV;
;         knorm_item(a, l, r, wave, lane);
.LBB0_232:
	s_or_b64 exec, exec, s[0:1]
	s_waitcnt lgkmcnt(0)
	s_barrier
	ds_read_b32 v0, v120
	s_movk_i32 s0, 0x2ff
	s_waitcnt lgkmcnt(0)
	v_cmp_lt_i32_e32 vcc, s0, v0
	v_readfirstlane_b32 s33, v0
	s_mov_b64 s[0:1], -1
	s_cbranch_vccnz .LBB0_227
	s_cmpk_gt_i32 s33, 0x7f
	s_cbranch_scc0 .LBB0_262
	s_cmpk_gt_u32 s33, 0xff
	s_cbranch_scc0 .LBB0_243
	s_cmpk_gt_u32 s33, 0x1ff
	s_cbranch_scc0 .LBB0_239
	global_load_dword v8, v[66:67], off
	v_cmp_lt_i32_e32 vcc, v124, v123
	s_lshl_b32 s0, s33, 10
	s_add_i32 s24, s34, s0
	v_cndmask_b32_e32 v0, v122, v124, vcc
	v_cmp_lt_i32_e32 vcc, v125, v123
	v_lshlrev_b32_e32 v9, 2, v0
	s_mov_b32 s57, -16
	v_cndmask_b32_e32 v0, v122, v125, vcc
	v_cmp_lt_i32_e32 vcc, v126, v123
	v_lshlrev_b32_e32 v10, 2, v0
	s_nop 0
	v_cndmask_b32_e32 v0, v122, v126, vcc
	v_cmp_lt_i32_e32 vcc, v127, v123
	v_lshlrev_b32_e32 v11, 2, v0
	s_nop 0
	v_cndmask_b32_e32 v0, v122, v127, vcc
	v_cmp_lt_i32_e32 vcc, v128, v123
	v_lshlrev_b32_e32 v12, 2, v0
	s_nop 0
	v_cndmask_b32_e32 v0, v122, v128, vcc
	v_cmp_lt_i32_e32 vcc, v129, v123
	v_lshlrev_b32_e32 v13, 2, v0
	s_nop 0
	v_cndmask_b32_e32 v0, v122, v129, vcc
	v_lshlrev_b32_e32 v14, 2, v0
	v_mbcnt_lo_u32_b32 v186, -1, 0
	v_mbcnt_hi_u32_b32 v186, -1, v186
	v_and_b32_e32 v188, 31, v186
	v_lshlrev_b32_e32 v188, 3, v188
	v_lshlrev_b32_e32 v187, 2, v186
	v_sub_u32_e32 v188, v188, v187
	v_ashrrev_i32_e32 v189, 31, v188
	v_lshl_add_u64 v[188:189], v[66:67], 0, v[188:189]
	global_load_dwordx2 v[184:185], v[188:189], off
	v_lshlrev_b32_e32 v186, 1, v186
	v_mov_b32_e32 v187, 0
	v_lshl_add_u64 v[190:191], v[68:69], 0, v[186:187]
	v_lshl_add_u64 v[192:193], v[70:71], 0, v[186:187]
	v_mov_b32_e32 v194, 0x7060302
	v_mov_b32_e32 v195, s20
	v_lshl_add_u64 v[196:197], v[64:65], 0, v[186:187]
	v_mov_b32_e32 v198, s47
	v_mov_b32_e32 v199, 0
	v_lshl_add_u64 v[196:197], v[196:197], 0, v[198:199]
.LBB0_237:
	s_add_i32 s0, s24, s57
	s_add_i32 s0, s0, 0xfff80010
	s_ashr_i32 s4, s0, 2
	s_ashr_i32 s5, s4, 31
	s_mul_i32 s0, s4, 0x1a00
	s_mul_hi_i32 s1, s4, 0x1a00
	s_add_u32 s0, s92, s0
	s_addc_u32 s1, s93, s1
	s_lshl_b64 s[30:31], s[4:5], 8
	v_lshl_add_u64 v[0:1], s[0:1], 0, v[196:197]
	global_load_dword v4, v[0:1], off offset:1024
	global_load_dword v6, v[0:1], off offset:1536
	s_add_u32 s0, s0, 0x1a00
	s_addc_u32 s1, s1, 0
	v_lshl_add_u64 v[2:3], s[0:1], 0, v[196:197]
	global_load_dword v27, v[2:3], off offset:1024
	global_load_dword v28, v[2:3], off offset:1536
	s_add_u32 s0, s0, 0x1a00
	s_addc_u32 s1, s1, 0
	v_lshl_add_u64 v[0:1], s[0:1], 0, v[196:197]
	global_load_dword v25, v[0:1], off offset:1024
	global_load_dword v26, v[0:1], off offset:1536
	s_add_u32 s0, s0, 0x1a00
	s_addc_u32 s1, s1, 0
	v_lshl_add_u64 v[2:3], s[0:1], 0, v[196:197]
	global_load_dword v23, v[2:3], off offset:1024
	global_load_dword v24, v[2:3], off offset:1536
	v_lshl_add_u64 v[200:201], v[190:191], 0, s[30:31]
	v_lshl_add_u64 v[202:203], v[192:193], 0, s[30:31]
	s_waitcnt vmcnt(4)
	v_lshlrev_b32_e32 v220, 16, v4
	v_and_b32_e32 v221, 0xffff0000, v4
	v_lshlrev_b32_e32 v228, 16, v6
	v_and_b32_e32 v229, 0xffff0000, v6
	v_lshlrev_b32_e32 v236, 16, v27
	v_and_b32_e32 v237, 0xffff0000, v27
	v_lshlrev_b32_e32 v244, 16, v28
	v_and_b32_e32 v245, 0xffff0000, v28
	v_mul_f32_e32 v224, v220, v220
	v_mul_f32_e32 v225, v221, v221
	v_mul_f32_e32 v232, v228, v228
	v_mul_f32_e32 v233, v229, v229
	v_mul_f32_e32 v240, v236, v236
	v_mul_f32_e32 v241, v237, v237
	v_mul_f32_e32 v248, v244, v244
	v_mul_f32_e32 v249, v245, v245
	v_fma_f32 v222, v220, v220, v225
	v_fma_f32 v223, v221, v221, v224
	v_fma_f32 v230, v228, v228, v233
	v_fma_f32 v231, v229, v229, v232
	v_fma_f32 v238, v236, v236, v241
	v_fma_f32 v239, v237, v237, v240
	v_fma_f32 v246, v244, v244, v249
	v_fma_f32 v247, v245, v245, v248
	v_add_f32_dpp v222, v222, v222 quad_perm:[1,0,3,2] row_mask:0xf bank_mask:0xf
	v_add_f32_dpp v223, v223, v223 quad_perm:[1,0,3,2] row_mask:0xf bank_mask:0xf
	v_add_f32_dpp v230, v230, v230 quad_perm:[1,0,3,2] row_mask:0xf bank_mask:0xf
	v_add_f32_dpp v231, v231, v231 quad_perm:[1,0,3,2] row_mask:0xf bank_mask:0xf
	v_add_f32_dpp v238, v238, v238 quad_perm:[1,0,3,2] row_mask:0xf bank_mask:0xf
	v_add_f32_dpp v239, v239, v239 quad_perm:[1,0,3,2] row_mask:0xf bank_mask:0xf
	v_add_f32_dpp v246, v246, v246 quad_perm:[1,0,3,2] row_mask:0xf bank_mask:0xf
	v_add_f32_dpp v247, v247, v247 quad_perm:[1,0,3,2] row_mask:0xf bank_mask:0xf
	v_add_f32_dpp v222, v222, v222 quad_perm:[2,3,0,1] row_mask:0xf bank_mask:0xf
	v_add_f32_dpp v223, v223, v223 quad_perm:[2,3,0,1] row_mask:0xf bank_mask:0xf
	v_add_f32_dpp v230, v230, v230 quad_perm:[2,3,0,1] row_mask:0xf bank_mask:0xf
	v_add_f32_dpp v231, v231, v231 quad_perm:[2,3,0,1] row_mask:0xf bank_mask:0xf
	v_add_f32_dpp v238, v238, v238 quad_perm:[2,3,0,1] row_mask:0xf bank_mask:0xf
	v_add_f32_dpp v239, v239, v239 quad_perm:[2,3,0,1] row_mask:0xf bank_mask:0xf
	v_add_f32_dpp v246, v246, v246 quad_perm:[2,3,0,1] row_mask:0xf bank_mask:0xf
	v_add_f32_dpp v247, v247, v247 quad_perm:[2,3,0,1] row_mask:0xf bank_mask:0xf
	ds_bpermute_b32 v224, v11, v222
	ds_bpermute_b32 v225, v11, v223
	ds_bpermute_b32 v232, v11, v230
	ds_bpermute_b32 v233, v11, v231
	ds_bpermute_b32 v240, v11, v238
	ds_bpermute_b32 v241, v11, v239
	ds_bpermute_b32 v248, v11, v246
	ds_bpermute_b32 v249, v11, v247
	s_waitcnt lgkmcnt(0)
; __device__ __forceinline__ float bf2f(unsigned short u) { return __uint_as_float((unsigned)u << 16); }
; __device__ __forceinline__ unsigned f2bf(float f) { unsigned u = __float_as_uint(f); return (u + 0x7fffu + ((u >> 16) & 1u)) >> 16; }
; __device__ __forceinline__ void knorm_item(const KArgs& a, int l, int item, int wave, int lane) {
;     ...
;         for (int i = 0; i < 16; ++i) { const int task = item * 1024 + wave * 128 + r0 + i, row = task >> 2, which = (task >> 1) & 1, g = task & 1;
;             v[i] = bf2f(Z[(size_t)row * ZW + (which ? ZC_KW : ZC_KS) + g * 64 + lane]); }
; #pragma unroll
;         for (int i = 0; i < 16; ++i) { const int task = item * 1024 + wave * 128 + r0 + i, row = task >> 2, which = (task >> 1) & 1, g = task & 1;
;             const float rstd = rsqrtf(wave_sum(v[i] * v[i]) * (1.f / 64.f) + EPS);
;             bf16_t* dst = (bf16_t*)(a.ws + (which ? WS_KWN : WS_KSN));
;             dst[(size_t)row * 128 + g * 64 + lane] = (bf16_t)f2bf(v[i] * rstd * kg); }
	v_add_f32_e32 v222, v222, v224
	v_add_f32_e32 v223, v223, v225
	v_add_f32_e32 v230, v230, v232
	v_add_f32_e32 v231, v231, v233
	v_add_f32_e32 v238, v238, v240
	v_add_f32_e32 v239, v239, v241
	v_add_f32_e32 v246, v246, v248
	v_add_f32_e32 v247, v247, v249
	v_add_f32_dpp v222, v222, v222 row_ror:8 row_mask:0xf bank_mask:0xf
	v_add_f32_dpp v223, v223, v223 row_ror:8 row_mask:0xf bank_mask:0xf
	v_add_f32_dpp v230, v230, v230 row_ror:8 row_mask:0xf bank_mask:0xf
	v_add_f32_dpp v231, v231, v231 row_ror:8 row_mask:0xf bank_mask:0xf
	v_add_f32_dpp v238, v238, v238 row_ror:8 row_mask:0xf bank_mask:0xf
	v_add_f32_dpp v239, v239, v239 row_ror:8 row_mask:0xf bank_mask:0xf
	v_add_f32_dpp v246, v246, v246 row_ror:8 row_mask:0xf bank_mask:0xf
	v_add_f32_dpp v247, v247, v247 row_ror:8 row_mask:0xf bank_mask:0xf
	ds_bpermute_b32 v224, v13, v222
	ds_bpermute_b32 v225, v13, v223
	ds_bpermute_b32 v232, v13, v230
	ds_bpermute_b32 v233, v13, v231
	ds_bpermute_b32 v240, v13, v238
	ds_bpermute_b32 v241, v13, v239
	ds_bpermute_b32 v248, v13, v246
	ds_bpermute_b32 v249, v13, v247
	s_waitcnt lgkmcnt(0)
	v_add_f32_e32 v222, v222, v224
	v_add_f32_e32 v223, v223, v225
	v_add_f32_e32 v230, v230, v232
	v_add_f32_e32 v231, v231, v233
	v_add_f32_e32 v238, v238, v240
	v_add_f32_e32 v239, v239, v241
	v_add_f32_e32 v246, v246, v248
	v_add_f32_e32 v247, v247, v249
	v_fma_f32 v222, v222, s22, v195
	v_fma_f32 v223, v223, s22, v195
	v_fma_f32 v230, v230, s22, v195
	v_fma_f32 v231, v231, s22, v195
	v_fma_f32 v238, v238, s22, v195
	v_fma_f32 v239, v239, s22, v195
	v_fma_f32 v246, v246, s22, v195
	v_fma_f32 v247, v247, s22, v195
	v_mul_f32_e32 v226, 0x4b800000, v222
	v_mul_f32_e32 v227, 0x4b800000, v223
	v_cmp_gt_f32_e64 s[4:5], s48, v222
	v_cmp_gt_f32_e32 vcc, s48, v223
	s_nop 1
	v_cndmask_b32_e64 v222, v222, v226, s[4:5]
	v_cndmask_b32_e32 v223, v223, v227, vcc
	v_rsq_f32_e32 v222, v222
	v_rsq_f32_e32 v223, v223
	s_nop 0
	v_mul_f32_e32 v226, 0x45800000, v222
	v_mul_f32_e32 v227, 0x45800000, v223
	v_cndmask_b32_e64 v222, v222, v226, s[4:5]
	v_cndmask_b32_e32 v223, v223, v227, vcc
	v_mul_f32_e32 v220, v222, v220
	v_mul_f32_e32 v221, v223, v221
	v_mul_f32_e32 v220, v184, v220
	v_mul_f32_e32 v221, v185, v221
	v_bfe_u32 v226, v220, 16, 1
	v_bfe_u32 v227, v221, 16, 1
	v_add3_u32 v220, v220, v226, s49
	v_add3_u32 v221, v221, v227, s49
	v_perm_b32 v4, v221, v220, v194
	global_store_dword v[200:201], v4, off
	v_mul_f32_e32 v234, 0x4b800000, v230
	v_mul_f32_e32 v235, 0x4b800000, v231
	v_cmp_gt_f32_e64 s[4:5], s48, v230
	v_cmp_gt_f32_e32 vcc, s48, v231
	s_nop 1
	v_cndmask_b32_e64 v230, v230, v234, s[4:5]
	v_cndmask_b32_e32 v231, v231, v235, vcc
	v_rsq_f32_e32 v230, v230
	v_rsq_f32_e32 v231, v231
	s_nop 0
	v_mul_f32_e32 v234, 0x45800000, v230
	v_mul_f32_e32 v235, 0x45800000, v231
	v_cndmask_b32_e64 v230, v230, v234, s[4:5]
	v_cndmask_b32_e32 v231, v231, v235, vcc
	v_mul_f32_e32 v228, v230, v228
	v_mul_f32_e32 v229, v231, v229
	v_mul_f32_e32 v228, v184, v228
	v_mul_f32_e32 v229, v185, v229
	v_bfe_u32 v234, v228, 16, 1
	v_bfe_u32 v235, v229, 16, 1
	v_add3_u32 v228, v228, v234, s49
	v_add3_u32 v229, v229, v235, s49
	v_perm_b32 v6, v229, v228, v194
	global_store_dword v[202:203], v6, off
	v_mul_f32_e32 v242, 0x4b800000, v238
	v_mul_f32_e32 v243, 0x4b800000, v239
	v_cmp_gt_f32_e64 s[4:5], s48, v238
	v_cmp_gt_f32_e32 vcc, s48, v239
	s_nop 1
	v_cndmask_b32_e64 v238, v238, v242, s[4:5]
	v_cndmask_b32_e32 v239, v239, v243, vcc
	v_rsq_f32_e32 v238, v238
	v_rsq_f32_e32 v239, v239
	s_nop 0
	v_mul_f32_e32 v242, 0x45800000, v238
	v_mul_f32_e32 v243, 0x45800000, v239
	v_cndmask_b32_e64 v238, v238, v242, s[4:5]
	v_cndmask_b32_e32 v239, v239, v243, vcc
	v_mul_f32_e32 v236, v238, v236
	v_mul_f32_e32 v237, v239, v237
	v_mul_f32_e32 v236, v184, v236
	v_mul_f32_e32 v237, v185, v237
	v_bfe_u32 v242, v236, 16, 1
	v_bfe_u32 v243, v237, 16, 1
	v_add3_u32 v236, v236, v242, s49
	v_add3_u32 v237, v237, v243, s49
	v_perm_b32 v27, v237, v236, v194
	global_store_dword v[200:201], v27, off offset:256
	v_mul_f32_e32 v250, 0x4b800000, v246
	v_mul_f32_e32 v251, 0x4b800000, v247
	v_cmp_gt_f32_e64 s[4:5], s48, v246
	v_cmp_gt_f32_e32 vcc, s48, v247
	s_nop 1
	v_cndmask_b32_e64 v246, v246, v250, s[4:5]
	v_cndmask_b32_e32 v247, v247, v251, vcc
	v_rsq_f32_e32 v246, v246
	v_rsq_f32_e32 v247, v247
	s_nop 0
	v_mul_f32_e32 v250, 0x45800000, v246
	v_mul_f32_e32 v251, 0x45800000, v247
	v_cndmask_b32_e64 v246, v246, v250, s[4:5]
	v_cndmask_b32_e32 v247, v247, v251, vcc
	v_mul_f32_e32 v244, v246, v244
	v_mul_f32_e32 v245, v247, v245
	v_mul_f32_e32 v244, v184, v244
	v_mul_f32_e32 v245, v185, v245
	v_bfe_u32 v250, v244, 16, 1
	v_bfe_u32 v251, v245, 16, 1
	v_add3_u32 v244, v244, v250, s49
	v_add3_u32 v245, v245, v251, s49
	v_perm_b32 v28, v245, v244, v194
	global_store_dword v[202:203], v28, off offset:256
	s_waitcnt vmcnt(4)
; __device__ __forceinline__ float bf2f(unsigned short u) { return __uint_as_float((unsigned)u << 16); }
; __device__ __forceinline__ void knorm_item(const KArgs& a, int l, int item, int wave, int lane) {
;     ...
;         for (int i = 0; i < 16; ++i) { const int task = item * 1024 + wave * 128 + r0 + i, row = task >> 2, which = (task >> 1) & 1, g = task & 1;
;             v[i] = bf2f(Z[(size_t)row * ZW + (which ? ZC_KW : ZC_KS) + g * 64 + lane]); }
; #pragma unroll
;         for (int i = 0; i < 16; ++i) { const int task = item * 1024 + wave * 128 + r0 + i, row = task >> 2, which = (task >> 1) & 1, g = task & 1;
;             const float rstd = rsqrtf(wave_sum(v[i] * v[i]) * (1.f / 64.f) + EPS);
	v_lshlrev_b32_e32 v220, 16, v25
	v_and_b32_e32 v221, 0xffff0000, v25
	v_lshlrev_b32_e32 v228, 16, v26
	v_and_b32_e32 v229, 0xffff0000, v26
	v_lshlrev_b32_e32 v236, 16, v23
	v_and_b32_e32 v237, 0xffff0000, v23
	v_lshlrev_b32_e32 v244, 16, v24
	v_and_b32_e32 v245, 0xffff0000, v24
	v_mul_f32_e32 v224, v220, v220
	v_mul_f32_e32 v225, v221, v221
	v_mul_f32_e32 v232, v228, v228
	v_mul_f32_e32 v233, v229, v229
	v_mul_f32_e32 v240, v236, v236
	v_mul_f32_e32 v241, v237, v237
	v_mul_f32_e32 v248, v244, v244
	v_mul_f32_e32 v249, v245, v245
	v_fma_f32 v222, v220, v220, v225
	v_fma_f32 v223, v221, v221, v224
	v_fma_f32 v230, v228, v228, v233
	v_fma_f32 v231, v229, v229, v232
	v_fma_f32 v238, v236, v236, v241
	v_fma_f32 v239, v237, v237, v240
	v_fma_f32 v246, v244, v244, v249
	v_fma_f32 v247, v245, v245, v248
	v_add_f32_dpp v222, v222, v222 quad_perm:[1,0,3,2] row_mask:0xf bank_mask:0xf
	v_add_f32_dpp v223, v223, v223 quad_perm:[1,0,3,2] row_mask:0xf bank_mask:0xf
	v_add_f32_dpp v230, v230, v230 quad_perm:[1,0,3,2] row_mask:0xf bank_mask:0xf
	v_add_f32_dpp v231, v231, v231 quad_perm:[1,0,3,2] row_mask:0xf bank_mask:0xf
	v_add_f32_dpp v238, v238, v238 quad_perm:[1,0,3,2] row_mask:0xf bank_mask:0xf
	v_add_f32_dpp v239, v239, v239 quad_perm:[1,0,3,2] row_mask:0xf bank_mask:0xf
	v_add_f32_dpp v246, v246, v246 quad_perm:[1,0,3,2] row_mask:0xf bank_mask:0xf
	v_add_f32_dpp v247, v247, v247 quad_perm:[1,0,3,2] row_mask:0xf bank_mask:0xf
	v_add_f32_dpp v222, v222, v222 quad_perm:[2,3,0,1] row_mask:0xf bank_mask:0xf
	v_add_f32_dpp v223, v223, v223 quad_perm:[2,3,0,1] row_mask:0xf bank_mask:0xf
	v_add_f32_dpp v230, v230, v230 quad_perm:[2,3,0,1] row_mask:0xf bank_mask:0xf
	v_add_f32_dpp v231, v231, v231 quad_perm:[2,3,0,1] row_mask:0xf bank_mask:0xf
	v_add_f32_dpp v238, v238, v238 quad_perm:[2,3,0,1] row_mask:0xf bank_mask:0xf
	v_add_f32_dpp v239, v239, v239 quad_perm:[2,3,0,1] row_mask:0xf bank_mask:0xf
	v_add_f32_dpp v246, v246, v246 quad_perm:[2,3,0,1] row_mask:0xf bank_mask:0xf
	v_add_f32_dpp v247, v247, v247 quad_perm:[2,3,0,1] row_mask:0xf bank_mask:0xf
	ds_bpermute_b32 v224, v11, v222
	ds_bpermute_b32 v225, v11, v223
	ds_bpermute_b32 v232, v11, v230
	ds_bpermute_b32 v233, v11, v231
	ds_bpermute_b32 v240, v11, v238
	ds_bpermute_b32 v241, v11, v239
	ds_bpermute_b32 v248, v11, v246
	ds_bpermute_b32 v249, v11, v247
	s_waitcnt lgkmcnt(0)
	v_add_f32_e32 v222, v222, v224
	v_add_f32_e32 v223, v223, v225
	v_add_f32_e32 v230, v230, v232
	v_add_f32_e32 v231, v231, v233
	v_add_f32_e32 v238, v238, v240
	v_add_f32_e32 v239, v239, v241
	v_add_f32_e32 v246, v246, v248
	v_add_f32_e32 v247, v247, v249
	v_add_f32_dpp v222, v222, v222 row_ror:8 row_mask:0xf bank_mask:0xf
	v_add_f32_dpp v223, v223, v223 row_ror:8 row_mask:0xf bank_mask:0xf
	v_add_f32_dpp v230, v230, v230 row_ror:8 row_mask:0xf bank_mask:0xf
	v_add_f32_dpp v231, v231, v231 row_ror:8 row_mask:0xf bank_mask:0xf
	v_add_f32_dpp v238, v238, v238 row_ror:8 row_mask:0xf bank_mask:0xf
	v_add_f32_dpp v239, v239, v239 row_ror:8 row_mask:0xf bank_mask:0xf
	v_add_f32_dpp v246, v246, v246 row_ror:8 row_mask:0xf bank_mask:0xf
	v_add_f32_dpp v247, v247, v247 row_ror:8 row_mask:0xf bank_mask:0xf
	ds_bpermute_b32 v224, v13, v222
	ds_bpermute_b32 v225, v13, v223
	ds_bpermute_b32 v232, v13, v230
	ds_bpermute_b32 v233, v13, v231
	ds_bpermute_b32 v240, v13, v238
	ds_bpermute_b32 v241, v13, v239
	ds_bpermute_b32 v248, v13, v246
	ds_bpermute_b32 v249, v13, v247
	s_waitcnt lgkmcnt(0)
; __device__ __forceinline__ unsigned f2bf(float f) { unsigned u = __float_as_uint(f); return (u + 0x7fffu + ((u >> 16) & 1u)) >> 16; }
; __device__ __forceinline__ void knorm_item(const KArgs& a, int l, int item, int wave, int lane) {
;     ...
;     for (int r0 = 0; r0 < 128; r0 += 16) {
;     ...
;             const float rstd = rsqrtf(wave_sum(v[i] * v[i]) * (1.f / 64.f) + EPS);
;             bf16_t* dst = (bf16_t*)(a.ws + (which ? WS_KWN : WS_KSN));
;             dst[(size_t)row * 128 + g * 64 + lane] = (bf16_t)f2bf(v[i] * rstd * kg); }
	v_add_f32_e32 v222, v222, v224
	v_add_f32_e32 v223, v223, v225
	v_add_f32_e32 v230, v230, v232
	v_add_f32_e32 v231, v231, v233
	v_add_f32_e32 v238, v238, v240
	v_add_f32_e32 v239, v239, v241
	v_add_f32_e32 v246, v246, v248
	v_add_f32_e32 v247, v247, v249
	v_fma_f32 v222, v222, s22, v195
	v_fma_f32 v223, v223, s22, v195
	v_fma_f32 v230, v230, s22, v195
	v_fma_f32 v231, v231, s22, v195
	v_fma_f32 v238, v238, s22, v195
	v_fma_f32 v239, v239, s22, v195
	v_fma_f32 v246, v246, s22, v195
	v_fma_f32 v247, v247, s22, v195
	v_mul_f32_e32 v226, 0x4b800000, v222
	v_mul_f32_e32 v227, 0x4b800000, v223
	v_cmp_gt_f32_e64 s[4:5], s48, v222
	v_cmp_gt_f32_e32 vcc, s48, v223
	s_nop 1
	v_cndmask_b32_e64 v222, v222, v226, s[4:5]
	v_cndmask_b32_e32 v223, v223, v227, vcc
	v_rsq_f32_e32 v222, v222
	v_rsq_f32_e32 v223, v223
	s_nop 0
	v_mul_f32_e32 v226, 0x45800000, v222
	v_mul_f32_e32 v227, 0x45800000, v223
	v_cndmask_b32_e64 v222, v222, v226, s[4:5]
	v_cndmask_b32_e32 v223, v223, v227, vcc
	v_mul_f32_e32 v220, v222, v220
	v_mul_f32_e32 v221, v223, v221
	v_mul_f32_e32 v220, v184, v220
	v_mul_f32_e32 v221, v185, v221
	v_bfe_u32 v226, v220, 16, 1
	v_bfe_u32 v227, v221, 16, 1
	v_add3_u32 v220, v220, v226, s49
	v_add3_u32 v221, v221, v227, s49
	v_perm_b32 v25, v221, v220, v194
	global_store_dword v[200:201], v25, off offset:512
	v_mul_f32_e32 v234, 0x4b800000, v230
	v_mul_f32_e32 v235, 0x4b800000, v231
	v_cmp_gt_f32_e64 s[4:5], s48, v230
	v_cmp_gt_f32_e32 vcc, s48, v231
	s_nop 1
	v_cndmask_b32_e64 v230, v230, v234, s[4:5]
	v_cndmask_b32_e32 v231, v231, v235, vcc
	v_rsq_f32_e32 v230, v230
	v_rsq_f32_e32 v231, v231
	s_nop 0
	v_mul_f32_e32 v234, 0x45800000, v230
	v_mul_f32_e32 v235, 0x45800000, v231
	v_cndmask_b32_e64 v230, v230, v234, s[4:5]
	v_cndmask_b32_e32 v231, v231, v235, vcc
	v_mul_f32_e32 v228, v230, v228
	v_mul_f32_e32 v229, v231, v229
	v_mul_f32_e32 v228, v184, v228
	v_mul_f32_e32 v229, v185, v229
	v_bfe_u32 v234, v228, 16, 1
	v_bfe_u32 v235, v229, 16, 1
	v_add3_u32 v228, v228, v234, s49
	v_add3_u32 v229, v229, v235, s49
	v_perm_b32 v26, v229, v228, v194
	global_store_dword v[202:203], v26, off offset:512
	v_mul_f32_e32 v242, 0x4b800000, v238
	v_mul_f32_e32 v243, 0x4b800000, v239
	v_cmp_gt_f32_e64 s[4:5], s48, v238
	v_cmp_gt_f32_e32 vcc, s48, v239
	s_nop 1
	v_cndmask_b32_e64 v238, v238, v242, s[4:5]
	v_cndmask_b32_e32 v239, v239, v243, vcc
	v_rsq_f32_e32 v238, v238
	v_rsq_f32_e32 v239, v239
	s_nop 0
	v_mul_f32_e32 v242, 0x45800000, v238
	v_mul_f32_e32 v243, 0x45800000, v239
	v_cndmask_b32_e64 v238, v238, v242, s[4:5]
	v_cndmask_b32_e32 v239, v239, v243, vcc
	v_mul_f32_e32 v236, v238, v236
	v_mul_f32_e32 v237, v239, v237
	v_mul_f32_e32 v236, v184, v236
	v_mul_f32_e32 v237, v185, v237
	v_bfe_u32 v242, v236, 16, 1
	v_bfe_u32 v243, v237, 16, 1
	v_add3_u32 v236, v236, v242, s49
	v_add3_u32 v237, v237, v243, s49
	v_perm_b32 v23, v237, v236, v194
	global_store_dword v[200:201], v23, off offset:768
	v_mul_f32_e32 v250, 0x4b800000, v246
	v_mul_f32_e32 v251, 0x4b800000, v247
	v_cmp_gt_f32_e64 s[4:5], s48, v246
	v_cmp_gt_f32_e32 vcc, s48, v247
	s_nop 1
	v_cndmask_b32_e64 v246, v246, v250, s[4:5]
	v_cndmask_b32_e32 v247, v247, v251, vcc
	v_rsq_f32_e32 v246, v246
	v_rsq_f32_e32 v247, v247
	s_nop 0
	v_mul_f32_e32 v250, 0x45800000, v246
	v_mul_f32_e32 v251, 0x45800000, v247
	v_cndmask_b32_e64 v246, v246, v250, s[4:5]
	v_cndmask_b32_e32 v247, v247, v251, vcc
	v_mul_f32_e32 v244, v246, v244
	v_mul_f32_e32 v245, v247, v245
	v_mul_f32_e32 v244, v184, v244
	v_mul_f32_e32 v245, v185, v245
	v_bfe_u32 v250, v244, 16, 1
	v_bfe_u32 v251, v245, 16, 1
	v_add3_u32 v244, v244, v250, s49
	v_add3_u32 v245, v245, v251, s49
	v_perm_b32 v24, v245, v244, v194
	global_store_dword v[202:203], v24, off offset:768
	s_add_i32 s57, s57, 16
	s_cmpk_gt_u32 s57, 0x6f
	s_cbranch_scc0 .LBB0_237
	s_mov_b64 s[0:1], 0

; __device__ __forceinline__ float bf2f(unsigned short u) { return __uint_as_float((unsigned)u << 16); }
; __device__ __forceinline__ void knorm_item(const KArgs& a, int l, int item, int wave, int lane) {
;     const bf16_t* Z = (const bf16_t*)(a.ws + WS_Z);
;     const float kg = a.in[I_KN][l * 64 + lane];
;     for (int r0 = 0; r0 < 128; r0 += 16) {
;         float v[16];
; #pragma unroll
;         for (int i = 0; i < 16; ++i) { const int task = item * 1024 + wave * 128 + r0 + i, row = task >> 2, which = (task >> 1) & 1, g = task & 1;
;             v[i] = bf2f(Z[(size_t)row * ZW + (which ? ZC_KW : ZC_KS) + g * 64 + lane]); }
; __device__ __forceinline__ void phase_mix1(const KArgs& a, int l, LAS unsigned char* lds, int wave, int lane, int ci) {
;     ...
;     for (;;) {
;         __syncthreads();
;         if (threadIdx.x == 0) *slot = (int)atomicAdd(ctr, 1u);
;         __syncthreads();
;         int r = *slot;
;         if (r >= N_R0 + N_CMP + N_CONV + N_KN) break;
;         if (r < N_R0) { ret0_item(a, l, r, lds, wave, lane); continue; } r -= N_R0;
;         if (r < N_CMP) { cmp_mfma_item(a, l, r, lds, wave, lane); continue; } r -= N_CMP;
;         if (r < N_CONV) { conv_item(a, l, r); continue; } r -= N_CONV;
;         knorm_item(a, l, r, wave, lane);
.LBB0_1033:
	s_or_b64 exec, exec, s[0:1]
	s_waitcnt lgkmcnt(0)
	s_barrier
	ds_read_b32 v0, v120
	s_movk_i32 s0, 0x2ff
	s_waitcnt lgkmcnt(0)
	v_cmp_lt_i32_e32 vcc, s0, v0
	v_readfirstlane_b32 s33, v0
	s_mov_b64 s[0:1], -1
	s_cbranch_vccnz .LBB0_1028
	s_cmpk_gt_i32 s33, 0x7f
	s_cbranch_scc0 .LBB0_1063
	s_cmpk_gt_u32 s33, 0xff
	s_cbranch_scc0 .LBB0_1044
	s_cmpk_gt_u32 s33, 0x1ff
	s_cbranch_scc0 .LBB0_1040
	global_load_dword v8, v[66:67], off offset:256
	v_cmp_lt_i32_e32 vcc, v124, v123
	s_lshl_b32 s0, s33, 10
	s_add_i32 s30, s40, s0
	v_cndmask_b32_e32 v0, v122, v124, vcc
	v_cmp_lt_i32_e32 vcc, v125, v123
	v_lshlrev_b32_e32 v9, 2, v0
	s_mov_b32 s63, -16
	v_cndmask_b32_e32 v0, v122, v125, vcc
	v_cmp_lt_i32_e32 vcc, v126, v123
	v_lshlrev_b32_e32 v10, 2, v0
	s_nop 0
	v_cndmask_b32_e32 v0, v122, v126, vcc
	v_cmp_lt_i32_e32 vcc, v127, v123
	v_lshlrev_b32_e32 v11, 2, v0
	s_nop 0
	v_cndmask_b32_e32 v0, v122, v127, vcc
	v_cmp_lt_i32_e32 vcc, v128, v123
	v_lshlrev_b32_e32 v12, 2, v0
	s_nop 0
	v_cndmask_b32_e32 v0, v122, v128, vcc
	v_cmp_lt_i32_e32 vcc, v129, v123
	v_lshlrev_b32_e32 v13, 2, v0
	s_nop 0
	v_cndmask_b32_e32 v0, v122, v129, vcc
	v_lshlrev_b32_e32 v14, 2, v0
	v_mbcnt_lo_u32_b32 v186, -1, 0
	v_mbcnt_hi_u32_b32 v186, -1, v186
	v_and_b32_e32 v188, 31, v186
	v_lshlrev_b32_e32 v188, 3, v188
	v_lshlrev_b32_e32 v187, 2, v186
	v_sub_u32_e32 v188, v188, v187
	v_ashrrev_i32_e32 v189, 31, v188
	v_lshl_add_u64 v[188:189], v[66:67], 0, v[188:189]
	global_load_dwordx2 v[184:185], v[188:189], off offset:256
	v_lshlrev_b32_e32 v186, 1, v186
	v_mov_b32_e32 v187, 0
	v_lshl_add_u64 v[190:191], v[68:69], 0, v[186:187]
	v_lshl_add_u64 v[192:193], v[70:71], 0, v[186:187]
	v_mov_b32_e32 v194, 0x7060302
	v_mov_b32_e32 v195, s26
	v_lshl_add_u64 v[196:197], v[64:65], 0, v[186:187]
	v_mov_b32_e32 v198, s53
	v_mov_b32_e32 v199, 0
	v_lshl_add_u64 v[196:197], v[196:197], 0, v[198:199]
.LBB0_1038:
	s_add_i32 s0, s30, s63
	s_add_i32 s0, s0, 0xfff80010
	s_ashr_i32 s4, s0, 2
	s_ashr_i32 s5, s4, 31
	s_mul_i32 s0, s4, 0x1a00
	s_mul_hi_i32 s1, s4, 0x1a00
	s_add_u32 s0, s92, s0
	s_addc_u32 s1, s93, s1
	s_lshl_b64 s[38:39], s[4:5], 8
	v_lshl_add_u64 v[0:1], s[0:1], 0, v[196:197]
	global_load_dword v4, v[0:1], off offset:1024
	global_load_dword v6, v[0:1], off offset:1536
	s_add_u32 s0, s0, 0x1a00
	s_addc_u32 s1, s1, 0
	v_lshl_add_u64 v[2:3], s[0:1], 0, v[196:197]
	global_load_dword v27, v[2:3], off offset:1024
	global_load_dword v28, v[2:3], off offset:1536
	s_add_u32 s0, s0, 0x1a00
	s_addc_u32 s1, s1, 0
	v_lshl_add_u64 v[0:1], s[0:1], 0, v[196:197]
	global_load_dword v25, v[0:1], off offset:1024
	global_load_dword v26, v[0:1], off offset:1536
	s_add_u32 s0, s0, 0x1a00
	s_addc_u32 s1, s1, 0
	v_lshl_add_u64 v[2:3], s[0:1], 0, v[196:197]
	global_load_dword v23, v[2:3], off offset:1024
	global_load_dword v24, v[2:3], off offset:1536
	v_lshl_add_u64 v[200:201], v[190:191], 0, s[38:39]
	v_lshl_add_u64 v[202:203], v[192:193], 0, s[38:39]
	s_waitcnt vmcnt(4)
	v_lshlrev_b32_e32 v220, 16, v4
	v_and_b32_e32 v221, 0xffff0000, v4
	v_lshlrev_b32_e32 v228, 16, v6
	v_and_b32_e32 v229, 0xffff0000, v6
	v_lshlrev_b32_e32 v236, 16, v27
	v_and_b32_e32 v237, 0xffff0000, v27
	v_lshlrev_b32_e32 v244, 16, v28
	v_and_b32_e32 v245, 0xffff0000, v28
	v_mul_f32_e32 v224, v220, v220
	v_mul_f32_e32 v225, v221, v221
	v_mul_f32_e32 v232, v228, v228
	v_mul_f32_e32 v233, v229, v229
	v_mul_f32_e32 v240, v236, v236
	v_mul_f32_e32 v241, v237, v237
	v_mul_f32_e32 v248, v244, v244
	v_mul_f32_e32 v249, v245, v245
	v_fma_f32 v222, v220, v220, v225
	v_fma_f32 v223, v221, v221, v224
	v_fma_f32 v230, v228, v228, v233
	v_fma_f32 v231, v229, v229, v232
	v_fma_f32 v238, v236, v236, v241
	v_fma_f32 v239, v237, v237, v240
	v_fma_f32 v246, v244, v244, v249
	v_fma_f32 v247, v245, v245, v248
	v_add_f32_dpp v222, v222, v222 quad_perm:[1,0,3,2] row_mask:0xf bank_mask:0xf
	v_add_f32_dpp v223, v223, v223 quad_perm:[1,0,3,2] row_mask:0xf bank_mask:0xf
	v_add_f32_dpp v230, v230, v230 quad_perm:[1,0,3,2] row_mask:0xf bank_mask:0xf
	v_add_f32_dpp v231, v231, v231 quad_perm:[1,0,3,2] row_mask:0xf bank_mask:0xf
	v_add_f32_dpp v238, v238, v238 quad_perm:[1,0,3,2] row_mask:0xf bank_mask:0xf
	v_add_f32_dpp v239, v239, v239 quad_perm:[1,0,3,2] row_mask:0xf bank_mask:0xf
	v_add_f32_dpp v246, v246, v246 quad_perm:[1,0,3,2] row_mask:0xf bank_mask:0xf
	v_add_f32_dpp v247, v247, v247 quad_perm:[1,0,3,2] row_mask:0xf bank_mask:0xf
	v_add_f32_dpp v222, v222, v222 quad_perm:[2,3,0,1] row_mask:0xf bank_mask:0xf
	v_add_f32_dpp v223, v223, v223 quad_perm:[2,3,0,1] row_mask:0xf bank_mask:0xf
	v_add_f32_dpp v230, v230, v230 quad_perm:[2,3,0,1] row_mask:0xf bank_mask:0xf
	v_add_f32_dpp v231, v231, v231 quad_perm:[2,3,0,1] row_mask:0xf bank_mask:0xf
	v_add_f32_dpp v238, v238, v238 quad_perm:[2,3,0,1] row_mask:0xf bank_mask:0xf
	v_add_f32_dpp v239, v239, v239 quad_perm:[2,3,0,1] row_mask:0xf bank_mask:0xf
	v_add_f32_dpp v246, v246, v246 quad_perm:[2,3,0,1] row_mask:0xf bank_mask:0xf
	v_add_f32_dpp v247, v247, v247 quad_perm:[2,3,0,1] row_mask:0xf bank_mask:0xf
	ds_bpermute_b32 v224, v11, v222
	ds_bpermute_b32 v225, v11, v223
	ds_bpermute_b32 v232, v11, v230
	ds_bpermute_b32 v233, v11, v231
	ds_bpermute_b32 v240, v11, v238
	ds_bpermute_b32 v241, v11, v239
	ds_bpermute_b32 v248, v11, v246
	ds_bpermute_b32 v249, v11, v247
	s_waitcnt lgkmcnt(0)
; __device__ __forceinline__ float bf2f(unsigned short u) { return __uint_as_float((unsigned)u << 16); }
; __device__ __forceinline__ unsigned f2bf(float f) { unsigned u = __float_as_uint(f); return (u + 0x7fffu + ((u >> 16) & 1u)) >> 16; }
; __device__ __forceinline__ void knorm_item(const KArgs& a, int l, int item, int wave, int lane) {
;     ...
;         for (int i = 0; i < 16; ++i) { const int task = item * 1024 + wave * 128 + r0 + i, row = task >> 2, which = (task >> 1) & 1, g = task & 1;
;             v[i] = bf2f(Z[(size_t)row * ZW + (which ? ZC_KW : ZC_KS) + g * 64 + lane]); }
; #pragma unroll
;         for (int i = 0; i < 16; ++i) { const int task = item * 1024 + wave * 128 + r0 + i, row = task >> 2, which = (task >> 1) & 1, g = task & 1;
;             const float rstd = rsqrtf(wave_sum(v[i] * v[i]) * (1.f / 64.f) + EPS);
;             bf16_t* dst = (bf16_t*)(a.ws + (which ? WS_KWN : WS_KSN));
;             dst[(size_t)row * 128 + g * 64 + lane] = (bf16_t)f2bf(v[i] * rstd * kg); }
	v_add_f32_e32 v222, v222, v224
	v_add_f32_e32 v223, v223, v225
	v_add_f32_e32 v230, v230, v232
	v_add_f32_e32 v231, v231, v233
	v_add_f32_e32 v238, v238, v240
	v_add_f32_e32 v239, v239, v241
	v_add_f32_e32 v246, v246, v248
	v_add_f32_e32 v247, v247, v249
	v_add_f32_dpp v222, v222, v222 row_ror:8 row_mask:0xf bank_mask:0xf
	v_add_f32_dpp v223, v223, v223 row_ror:8 row_mask:0xf bank_mask:0xf
	v_add_f32_dpp v230, v230, v230 row_ror:8 row_mask:0xf bank_mask:0xf
	v_add_f32_dpp v231, v231, v231 row_ror:8 row_mask:0xf bank_mask:0xf
	v_add_f32_dpp v238, v238, v238 row_ror:8 row_mask:0xf bank_mask:0xf
	v_add_f32_dpp v239, v239, v239 row_ror:8 row_mask:0xf bank_mask:0xf
	v_add_f32_dpp v246, v246, v246 row_ror:8 row_mask:0xf bank_mask:0xf
	v_add_f32_dpp v247, v247, v247 row_ror:8 row_mask:0xf bank_mask:0xf
	ds_bpermute_b32 v224, v13, v222
	ds_bpermute_b32 v225, v13, v223
	ds_bpermute_b32 v232, v13, v230
	ds_bpermute_b32 v233, v13, v231
	ds_bpermute_b32 v240, v13, v238
	ds_bpermute_b32 v241, v13, v239
	ds_bpermute_b32 v248, v13, v246
	ds_bpermute_b32 v249, v13, v247
	s_waitcnt lgkmcnt(0)
	v_add_f32_e32 v222, v222, v224
	v_add_f32_e32 v223, v223, v225
	v_add_f32_e32 v230, v230, v232
	v_add_f32_e32 v231, v231, v233
	v_add_f32_e32 v238, v238, v240
	v_add_f32_e32 v239, v239, v241
	v_add_f32_e32 v246, v246, v248
	v_add_f32_e32 v247, v247, v249
	v_fma_f32 v222, v222, s28, v195
	v_fma_f32 v223, v223, s28, v195
	v_fma_f32 v230, v230, s28, v195
	v_fma_f32 v231, v231, s28, v195
	v_fma_f32 v238, v238, s28, v195
	v_fma_f32 v239, v239, s28, v195
	v_fma_f32 v246, v246, s28, v195
	v_fma_f32 v247, v247, s28, v195
	v_mul_f32_e32 v226, 0x4b800000, v222
	v_mul_f32_e32 v227, 0x4b800000, v223
	v_cmp_gt_f32_e64 s[4:5], s54, v222
	v_cmp_gt_f32_e32 vcc, s54, v223
	s_nop 1
	v_cndmask_b32_e64 v222, v222, v226, s[4:5]
	v_cndmask_b32_e32 v223, v223, v227, vcc
	v_rsq_f32_e32 v222, v222
	v_rsq_f32_e32 v223, v223
	s_nop 0
	v_mul_f32_e32 v226, 0x45800000, v222
	v_mul_f32_e32 v227, 0x45800000, v223
	v_cndmask_b32_e64 v222, v222, v226, s[4:5]
	v_cndmask_b32_e32 v223, v223, v227, vcc
	v_mul_f32_e32 v220, v222, v220
	v_mul_f32_e32 v221, v223, v221
	v_mul_f32_e32 v220, v184, v220
	v_mul_f32_e32 v221, v185, v221
	v_bfe_u32 v226, v220, 16, 1
	v_bfe_u32 v227, v221, 16, 1
	v_add3_u32 v220, v220, v226, s55
	v_add3_u32 v221, v221, v227, s55
	v_perm_b32 v4, v221, v220, v194
	global_store_dword v[200:201], v4, off
	v_mul_f32_e32 v234, 0x4b800000, v230
	v_mul_f32_e32 v235, 0x4b800000, v231
	v_cmp_gt_f32_e64 s[4:5], s54, v230
	v_cmp_gt_f32_e32 vcc, s54, v231
	s_nop 1
	v_cndmask_b32_e64 v230, v230, v234, s[4:5]
	v_cndmask_b32_e32 v231, v231, v235, vcc
	v_rsq_f32_e32 v230, v230
	v_rsq_f32_e32 v231, v231
	s_nop 0
	v_mul_f32_e32 v234, 0x45800000, v230
	v_mul_f32_e32 v235, 0x45800000, v231
	v_cndmask_b32_e64 v230, v230, v234, s[4:5]
	v_cndmask_b32_e32 v231, v231, v235, vcc
	v_mul_f32_e32 v228, v230, v228
	v_mul_f32_e32 v229, v231, v229
	v_mul_f32_e32 v228, v184, v228
	v_mul_f32_e32 v229, v185, v229
	v_bfe_u32 v234, v228, 16, 1
	v_bfe_u32 v235, v229, 16, 1
	v_add3_u32 v228, v228, v234, s55
	v_add3_u32 v229, v229, v235, s55
	v_perm_b32 v6, v229, v228, v194
	global_store_dword v[202:203], v6, off
	v_mul_f32_e32 v242, 0x4b800000, v238
	v_mul_f32_e32 v243, 0x4b800000, v239
	v_cmp_gt_f32_e64 s[4:5], s54, v238
	v_cmp_gt_f32_e32 vcc, s54, v239
	s_nop 1
	v_cndmask_b32_e64 v238, v238, v242, s[4:5]
	v_cndmask_b32_e32 v239, v239, v243, vcc
	v_rsq_f32_e32 v238, v238
	v_rsq_f32_e32 v239, v239
	s_nop 0
	v_mul_f32_e32 v242, 0x45800000, v238
	v_mul_f32_e32 v243, 0x45800000, v239
	v_cndmask_b32_e64 v238, v238, v242, s[4:5]
	v_cndmask_b32_e32 v239, v239, v243, vcc
	v_mul_f32_e32 v236, v238, v236
	v_mul_f32_e32 v237, v239, v237
	v_mul_f32_e32 v236, v184, v236
	v_mul_f32_e32 v237, v185, v237
	v_bfe_u32 v242, v236, 16, 1
	v_bfe_u32 v243, v237, 16, 1
	v_add3_u32 v236, v236, v242, s55
	v_add3_u32 v237, v237, v243, s55
	v_perm_b32 v27, v237, v236, v194
	global_store_dword v[200:201], v27, off offset:256
	v_mul_f32_e32 v250, 0x4b800000, v246
	v_mul_f32_e32 v251, 0x4b800000, v247
	v_cmp_gt_f32_e64 s[4:5], s54, v246
	v_cmp_gt_f32_e32 vcc, s54, v247
	s_nop 1
	v_cndmask_b32_e64 v246, v246, v250, s[4:5]
	v_cndmask_b32_e32 v247, v247, v251, vcc
	v_rsq_f32_e32 v246, v246
	v_rsq_f32_e32 v247, v247
	s_nop 0
	v_mul_f32_e32 v250, 0x45800000, v246
	v_mul_f32_e32 v251, 0x45800000, v247
	v_cndmask_b32_e64 v246, v246, v250, s[4:5]
	v_cndmask_b32_e32 v247, v247, v251, vcc
	v_mul_f32_e32 v244, v246, v244
	v_mul_f32_e32 v245, v247, v245
	v_mul_f32_e32 v244, v184, v244
	v_mul_f32_e32 v245, v185, v245
	v_bfe_u32 v250, v244, 16, 1
	v_bfe_u32 v251, v245, 16, 1
	v_add3_u32 v244, v244, v250, s55
	v_add3_u32 v245, v245, v251, s55
	v_perm_b32 v28, v245, v244, v194
	global_store_dword v[202:203], v28, off offset:256
	s_waitcnt vmcnt(4)
; __device__ __forceinline__ float bf2f(unsigned short u) { return __uint_as_float((unsigned)u << 16); }
; __device__ __forceinline__ void knorm_item(const KArgs& a, int l, int item, int wave, int lane) {
;     ...
;         for (int i = 0; i < 16; ++i) { const int task = item * 1024 + wave * 128 + r0 + i, row = task >> 2, which = (task >> 1) & 1, g = task & 1;
;             v[i] = bf2f(Z[(size_t)row * ZW + (which ? ZC_KW : ZC_KS) + g * 64 + lane]); }
; #pragma unroll
;         for (int i = 0; i < 16; ++i) { const int task = item * 1024 + wave * 128 + r0 + i, row = task >> 2, which = (task >> 1) & 1, g = task & 1;
;             const float rstd = rsqrtf(wave_sum(v[i] * v[i]) * (1.f / 64.f) + EPS);
	v_lshlrev_b32_e32 v220, 16, v25
	v_and_b32_e32 v221, 0xffff0000, v25
	v_lshlrev_b32_e32 v228, 16, v26
	v_and_b32_e32 v229, 0xffff0000, v26
	v_lshlrev_b32_e32 v236, 16, v23
	v_and_b32_e32 v237, 0xffff0000, v23
	v_lshlrev_b32_e32 v244, 16, v24
	v_and_b32_e32 v245, 0xffff0000, v24
	v_mul_f32_e32 v224, v220, v220
	v_mul_f32_e32 v225, v221, v221
	v_mul_f32_e32 v232, v228, v228
	v_mul_f32_e32 v233, v229, v229
	v_mul_f32_e32 v240, v236, v236
	v_mul_f32_e32 v241, v237, v237
	v_mul_f32_e32 v248, v244, v244
	v_mul_f32_e32 v249, v245, v245
	v_fma_f32 v222, v220, v220, v225
	v_fma_f32 v223, v221, v221, v224
	v_fma_f32 v230, v228, v228, v233
	v_fma_f32 v231, v229, v229, v232
	v_fma_f32 v238, v236, v236, v241
	v_fma_f32 v239, v237, v237, v240
	v_fma_f32 v246, v244, v244, v249
	v_fma_f32 v247, v245, v245, v248
	v_add_f32_dpp v222, v222, v222 quad_perm:[1,0,3,2] row_mask:0xf bank_mask:0xf
	v_add_f32_dpp v223, v223, v223 quad_perm:[1,0,3,2] row_mask:0xf bank_mask:0xf
	v_add_f32_dpp v230, v230, v230 quad_perm:[1,0,3,2] row_mask:0xf bank_mask:0xf
	v_add_f32_dpp v231, v231, v231 quad_perm:[1,0,3,2] row_mask:0xf bank_mask:0xf
	v_add_f32_dpp v238, v238, v238 quad_perm:[1,0,3,2] row_mask:0xf bank_mask:0xf
	v_add_f32_dpp v239, v239, v239 quad_perm:[1,0,3,2] row_mask:0xf bank_mask:0xf
	v_add_f32_dpp v246, v246, v246 quad_perm:[1,0,3,2] row_mask:0xf bank_mask:0xf
	v_add_f32_dpp v247, v247, v247 quad_perm:[1,0,3,2] row_mask:0xf bank_mask:0xf
	v_add_f32_dpp v222, v222, v222 quad_perm:[2,3,0,1] row_mask:0xf bank_mask:0xf
	v_add_f32_dpp v223, v223, v223 quad_perm:[2,3,0,1] row_mask:0xf bank_mask:0xf
	v_add_f32_dpp v230, v230, v230 quad_perm:[2,3,0,1] row_mask:0xf bank_mask:0xf
	v_add_f32_dpp v231, v231, v231 quad_perm:[2,3,0,1] row_mask:0xf bank_mask:0xf
	v_add_f32_dpp v238, v238, v238 quad_perm:[2,3,0,1] row_mask:0xf bank_mask:0xf
	v_add_f32_dpp v239, v239, v239 quad_perm:[2,3,0,1] row_mask:0xf bank_mask:0xf
	v_add_f32_dpp v246, v246, v246 quad_perm:[2,3,0,1] row_mask:0xf bank_mask:0xf
	v_add_f32_dpp v247, v247, v247 quad_perm:[2,3,0,1] row_mask:0xf bank_mask:0xf
	ds_bpermute_b32 v224, v11, v222
	ds_bpermute_b32 v225, v11, v223
	ds_bpermute_b32 v232, v11, v230
	ds_bpermute_b32 v233, v11, v231
	ds_bpermute_b32 v240, v11, v238
	ds_bpermute_b32 v241, v11, v239
	ds_bpermute_b32 v248, v11, v246
	ds_bpermute_b32 v249, v11, v247
	s_waitcnt lgkmcnt(0)
	v_add_f32_e32 v222, v222, v224
	v_add_f32_e32 v223, v223, v225
	v_add_f32_e32 v230, v230, v232
	v_add_f32_e32 v231, v231, v233
	v_add_f32_e32 v238, v238, v240
	v_add_f32_e32 v239, v239, v241
	v_add_f32_e32 v246, v246, v248
	v_add_f32_e32 v247, v247, v249
	v_add_f32_dpp v222, v222, v222 row_ror:8 row_mask:0xf bank_mask:0xf
	v_add_f32_dpp v223, v223, v223 row_ror:8 row_mask:0xf bank_mask:0xf
	v_add_f32_dpp v230, v230, v230 row_ror:8 row_mask:0xf bank_mask:0xf
	v_add_f32_dpp v231, v231, v231 row_ror:8 row_mask:0xf bank_mask:0xf
	v_add_f32_dpp v238, v238, v238 row_ror:8 row_mask:0xf bank_mask:0xf
	v_add_f32_dpp v239, v239, v239 row_ror:8 row_mask:0xf bank_mask:0xf
	v_add_f32_dpp v246, v246, v246 row_ror:8 row_mask:0xf bank_mask:0xf
	v_add_f32_dpp v247, v247, v247 row_ror:8 row_mask:0xf bank_mask:0xf
	ds_bpermute_b32 v224, v13, v222
	ds_bpermute_b32 v225, v13, v223
	ds_bpermute_b32 v232, v13, v230
	ds_bpermute_b32 v233, v13, v231
	ds_bpermute_b32 v240, v13, v238
	ds_bpermute_b32 v241, v13, v239
	ds_bpermute_b32 v248, v13, v246
	ds_bpermute_b32 v249, v13, v247
	s_waitcnt lgkmcnt(0)
; __device__ __forceinline__ unsigned f2bf(float f) { unsigned u = __float_as_uint(f); return (u + 0x7fffu + ((u >> 16) & 1u)) >> 16; }
; __device__ __forceinline__ void knorm_item(const KArgs& a, int l, int item, int wave, int lane) {
;     ...
;     for (int r0 = 0; r0 < 128; r0 += 16) {
;     ...
;             const float rstd = rsqrtf(wave_sum(v[i] * v[i]) * (1.f / 64.f) + EPS);
;             bf16_t* dst = (bf16_t*)(a.ws + (which ? WS_KWN : WS_KSN));
;             dst[(size_t)row * 128 + g * 64 + lane] = (bf16_t)f2bf(v[i] * rstd * kg); }
	v_add_f32_e32 v222, v222, v224
	v_add_f32_e32 v223, v223, v225
	v_add_f32_e32 v230, v230, v232
	v_add_f32_e32 v231, v231, v233
	v_add_f32_e32 v238, v238, v240
	v_add_f32_e32 v239, v239, v241
	v_add_f32_e32 v246, v246, v248
	v_add_f32_e32 v247, v247, v249
	v_fma_f32 v222, v222, s28, v195
	v_fma_f32 v223, v223, s28, v195
	v_fma_f32 v230, v230, s28, v195
	v_fma_f32 v231, v231, s28, v195
	v_fma_f32 v238, v238, s28, v195
	v_fma_f32 v239, v239, s28, v195
	v_fma_f32 v246, v246, s28, v195
	v_fma_f32 v247, v247, s28, v195
	v_mul_f32_e32 v226, 0x4b800000, v222
	v_mul_f32_e32 v227, 0x4b800000, v223
	v_cmp_gt_f32_e64 s[4:5], s54, v222
	v_cmp_gt_f32_e32 vcc, s54, v223
	s_nop 1
	v_cndmask_b32_e64 v222, v222, v226, s[4:5]
	v_cndmask_b32_e32 v223, v223, v227, vcc
	v_rsq_f32_e32 v222, v222
	v_rsq_f32_e32 v223, v223
	s_nop 0
	v_mul_f32_e32 v226, 0x45800000, v222
	v_mul_f32_e32 v227, 0x45800000, v223
	v_cndmask_b32_e64 v222, v222, v226, s[4:5]
	v_cndmask_b32_e32 v223, v223, v227, vcc
	v_mul_f32_e32 v220, v222, v220
	v_mul_f32_e32 v221, v223, v221
	v_mul_f32_e32 v220, v184, v220
	v_mul_f32_e32 v221, v185, v221
	v_bfe_u32 v226, v220, 16, 1
	v_bfe_u32 v227, v221, 16, 1
	v_add3_u32 v220, v220, v226, s55
	v_add3_u32 v221, v221, v227, s55
	v_perm_b32 v25, v221, v220, v194
	global_store_dword v[200:201], v25, off offset:512
	v_mul_f32_e32 v234, 0x4b800000, v230
	v_mul_f32_e32 v235, 0x4b800000, v231
	v_cmp_gt_f32_e64 s[4:5], s54, v230
	v_cmp_gt_f32_e32 vcc, s54, v231
	s_nop 1
	v_cndmask_b32_e64 v230, v230, v234, s[4:5]
	v_cndmask_b32_e32 v231, v231, v235, vcc
	v_rsq_f32_e32 v230, v230
	v_rsq_f32_e32 v231, v231
	s_nop 0
	v_mul_f32_e32 v234, 0x45800000, v230
	v_mul_f32_e32 v235, 0x45800000, v231
	v_cndmask_b32_e64 v230, v230, v234, s[4:5]
	v_cndmask_b32_e32 v231, v231, v235, vcc
	v_mul_f32_e32 v228, v230, v228
	v_mul_f32_e32 v229, v231, v229
	v_mul_f32_e32 v228, v184, v228
	v_mul_f32_e32 v229, v185, v229
	v_bfe_u32 v234, v228, 16, 1
	v_bfe_u32 v235, v229, 16, 1
	v_add3_u32 v228, v228, v234, s55
	v_add3_u32 v229, v229, v235, s55
	v_perm_b32 v26, v229, v228, v194
	global_store_dword v[202:203], v26, off offset:512
	v_mul_f32_e32 v242, 0x4b800000, v238
	v_mul_f32_e32 v243, 0x4b800000, v239
	v_cmp_gt_f32_e64 s[4:5], s54, v238
	v_cmp_gt_f32_e32 vcc, s54, v239
	s_nop 1
	v_cndmask_b32_e64 v238, v238, v242, s[4:5]
	v_cndmask_b32_e32 v239, v239, v243, vcc
	v_rsq_f32_e32 v238, v238
	v_rsq_f32_e32 v239, v239
	s_nop 0
	v_mul_f32_e32 v242, 0x45800000, v238
	v_mul_f32_e32 v243, 0x45800000, v239
	v_cndmask_b32_e64 v238, v238, v242, s[4:5]
	v_cndmask_b32_e32 v239, v239, v243, vcc
	v_mul_f32_e32 v236, v238, v236
	v_mul_f32_e32 v237, v239, v237
	v_mul_f32_e32 v236, v184, v236
	v_mul_f32_e32 v237, v185, v237
	v_bfe_u32 v242, v236, 16, 1
	v_bfe_u32 v243, v237, 16, 1
	v_add3_u32 v236, v236, v242, s55
	v_add3_u32 v237, v237, v243, s55
	v_perm_b32 v23, v237, v236, v194
	global_store_dword v[200:201], v23, off offset:768
	v_mul_f32_e32 v250, 0x4b800000, v246
	v_mul_f32_e32 v251, 0x4b800000, v247
	v_cmp_gt_f32_e64 s[4:5], s54, v246
	v_cmp_gt_f32_e32 vcc, s54, v247
	s_nop 1
	v_cndmask_b32_e64 v246, v246, v250, s[4:5]
	v_cndmask_b32_e32 v247, v247, v251, vcc
	v_rsq_f32_e32 v246, v246
	v_rsq_f32_e32 v247, v247
	s_nop 0
	v_mul_f32_e32 v250, 0x45800000, v246
	v_mul_f32_e32 v251, 0x45800000, v247
	v_cndmask_b32_e64 v246, v246, v250, s[4:5]
	v_cndmask_b32_e32 v247, v247, v251, vcc
	v_mul_f32_e32 v244, v246, v244
	v_mul_f32_e32 v245, v247, v245
	v_mul_f32_e32 v244, v184, v244
	v_mul_f32_e32 v245, v185, v245
	v_bfe_u32 v250, v244, 16, 1
	v_bfe_u32 v251, v245, 16, 1
	v_add3_u32 v244, v244, v250, s55
	v_add3_u32 v245, v245, v251, s55
	v_perm_b32 v24, v245, v244, v194
	global_store_dword v[202:203], v24, off offset:768
	s_add_i32 s63, s63, 16
	s_cmpk_gt_u32 s63, 0x6f
	s_cbranch_scc0 .LBB0_1038
	s_mov_b64 s[0:1], 0
